# k7 plus LDS-resident attention unit order table (tail lookup without a global round trip)
# speedup vs baseline: 1.0065x; 1.0053x over previous
; __device__ __forceinline__ int v_st(int k, int c) { const int kk = (k & ~0xC) | ((k & 4) << 1) | ((k & 8) >> 1); return ((kk >> 3) * 4 + (c >> 5)) * 512 + ((kk & 7) * 32 + (c & 31)) * 2; }
; #define LAS __attribute__((address_space(3)))
; #define lane lane_id()
; template <bool ROPE, bool ALIBI, int QP, int Q2P, int KP, int VP, int OP>
; __device__ __forceinline__ void attn_unit(const Unit& u, char* lds, const int wid) {
;     int lane; asm volatile("v_mbcnt_lo_u32_b32 %0, -1, 0\n\tv_mbcnt_hi_u32_b32 %0, -1, %0" : "=v"(lane));
;     const int tid = wid * 64 + lane, r32 = lane & 31, hi = lane >> 5;
;     int toff = 0;
;     if constexpr (ALIBI) {
;         const float* qs = u.qst + (4 * u.qb) * 2;
;         const float qn2 = fmaxf(fmaxf(qs[0], qs[2]), fmaxf(qs[4], qs[6])), mlb = fminf(fminf(qs[1], qs[3]), fminf(qs[5], qs[7]));
;         const int t = lane + 1, dmin = 256 * u.qb - 64 * t + 1;
;         const bool inr = t < 4 * u.qb + 5 && dmin > 0;
;         const float kn2v = inr ? u.kn2[t] : 0.f;
;         const float ub = sqrtf(qn2 * kn2v) * 1.001f + 0.01f + u.nslope2 * (float)dmin;
;         const unsigned long long bal = __ballot(inr && ub < mlb - 115.f);
;         const int t_lo = 1 + __builtin_ctzll(~bal);
;         toff = __builtin_amdgcn_readfirstlane((t_lo - 1) & ~1);
;     }
;     const int NT = 4 * u.qb + 5 - toff;
;     const int jq = 1 + 4 * u.qb + (wid >> 1);
;     char* V_lds = lds + OFF_V; char* K_lds = lds + OFF_K; char* K2_lds = lds + OFF_K2;
;     float* ws = (float*)(lds + OFF_WS) + wid * 64; float* li_l = ws, * al_l = ws + 32;
;     float m_reg = -1e30f, l_reg = 0; f32x16 o[4] = {};
;     const int sr = tid >> 4, sc = (tid & 15) * 8, vst0 = v_st(sr, sc), vst1 = v_st(32 + sr, sc), kws = KSWZ(sr, sc * 2);
;     const int sr2 = tid >> 3, sc2 = (tid & 7) * 8, k2ws = K2SWZ(sr2, sc2 * 2);
;     const int vb0 = (int)(uintptr_t)V_lds + v_rd_base(lane);
; __global__ void __launch_bounds__(NWAVES * 64, 2) hybrid_fwd(Args args) {
;     ...
;     if (IN(4)) {
;         unsigned* qctr = (unsigned*)(ws + WS_CTL) + 3600;
;         volatile LAS unsigned* qslot = (volatile LAS unsigned*)((LAS unsigned char*)lds + MISC_OFF) + 16;
;         if (tid == 0) { const unsigned t_ = __hip_atomic_fetch_add(qctr, 1u, __ATOMIC_RELAXED, __HIP_MEMORY_SCOPE_AGENT); qslot[0] = t_ < 3072u ? (unsigned)ATT_ORDER[t_] : 0xffffffffu; }
.LBB0_682:
	v_writelane_b32 v254, s8, 32
	s_nop 1
	v_writelane_b32 v254, s9, 33
	v_writelane_b32 v254, s87, 29
	v_writelane_b32 v254, s96, 22
	s_nop 1
	v_writelane_b32 v254, s97, 23
	s_or_b64 exec, exec, s[2:3]
	v_mbcnt_lo_u32_b32 v4, -1, 0
	v_mbcnt_hi_u32_b32 v4, -1, v4
	v_add_u32_e32 v4, s11, v4
	v_lshlrev_b32_e32 v4, 2, v4
	s_getpc_b64 s[0:1]
	s_add_u32 s0, s0, _ZL9ATT_ORDER@rel32@lo+4
	s_addc_u32 s1, s1, _ZL9ATT_ORDER@rel32@hi+12
	v_add_u32_e32 v8, 0x1000, v4
	global_load_dword v5, v4, s[0:1]
	global_load_dword v6, v4, s[0:1] offset:2048
	global_load_dword v7, v8, s[0:1]
	v_add_u32_e32 v8, 0x21400, v4
	s_waitcnt vmcnt(0)
	ds_write_b32 v8, v5
	ds_write_b32 v8, v6 offset:2048
	ds_write_b32 v8, v7 offset:4096
	s_add_u32 s69, s28, 0x38000000
	s_addc_u32 s44, s29, 0
	s_lshl_b32 s0, s11, 2
	s_add_i32 s90, s0, 0
	s_lshl_b32 s0, s95, 12
	s_add_i32 s91, s0, 0
	s_lshr_b32 s80, s92, 7
	s_mov_b32 s43, 0
	s_add_i32 s90, s90, 0x14000
	s_add_i32 s82, s91, 0x14800
	s_lshl_b32 s6, s95, 5
	s_cmpk_gt_u32 s92, 0xff
	s_mov_b32 s7, s43
	s_cselect_b64 s[46:47], -1, 0
	s_lshl_b64 s[0:1], s[6:7], 12
	v_writelane_b32 v254, s0, 6
	s_bfe_u32 s81, s95, 0x10001
	v_cndmask_b32_e64 v0, 0, 1, s[46:47]
	v_writelane_b32 v254, s1, 7
	s_lshr_b32 s1, s92, 8
	s_bfe_u32 s0, s92, 0x20006
	s_lshl_b32 s2, s1, 15
	s_cmp_lg_u32 0, -1
	s_cselect_b32 s3, 0, 0
	s_add_i32 s83, s3, s2
	s_lshl_b32 s2, s0, 13
	s_lshl_b32 s3, s0, 9
	s_add_i32 s94, s2, 0
	s_add_i32 s95, s3, 0
	s_lshl_b32 s4, s0, 12
	s_add_i32 s94, s94, 0x18000
	s_add_i32 s95, s95, 0x20800
	s_cmpk_lt_u32 s92, 0x100
	s_cselect_b64 s[2:3], -1, 0
	v_writelane_b32 v254, s2, 8
	v_mov_b32_e32 v2, 0
	s_movk_i32 s97, 0x70
	v_writelane_b32 v254, s3, 9
	s_mov_b32 s2, s6
	v_writelane_b32 v254, s2, 10
	s_mov_b32 s33, 0x2fe14000
	s_mov_b32 s70, 0x2fe04000
	v_writelane_b32 v254, s3, 11
	s_and_b32 s2, s6, 32
	s_cmp_lg_u32 s1, 1
	v_writelane_b32 v254, s2, 34
	s_cselect_b64 s[84:85], -1, 0
	s_and_b32 s2, s92, 0xffffff00
	s_add_i32 s2, s95, s2
	v_writelane_b32 v254, s2, 35
	s_lshl_b32 s5, s0, 16
	s_add_i32 s0, 0, 0x21180
	s_lshl_b32 s6, s1, 7
	v_writelane_b32 v254, s0, 18
	s_add_i32 s1, 0, 0x12000
	v_writelane_b32 v254, s1, 4
	s_lshl_b32 s1, s4, 1
	v_writelane_b32 v254, s1, 36
	s_lshl_b32 s1, s5, 1
	v_writelane_b32 v254, s1, 37
	s_lshl_b32 s1, s6, 1
	v_writelane_b32 v254, s1, 38
	s_add_i32 s8, s91, 0x10000
	v_mov_b32_e32 v217, s0
	v_cmp_ne_u32_e64 s[2:3], 1, v0
	s_add_i32 s96, 0, 0x10000
	s_mov_b32 s0, 0x4138aa3b
	s_mov_b64 s[86:87], 0x8000
	v_mov_b32_e32 v218, 0x260
	s_mov_b32 s41, 0x41000000
	v_mov_b32_e32 v219, 0xf149f2ca
	v_mov_b32_e32 v16, 0xff800000
	v_mov_b32_e32 v220, 0x42800000
	v_mov_b32_e32 v221, 0xc1800000
	v_mov_b32_e32 v222, 0xbf80
	v_writelane_b32 v254, s78, 39
	s_nop 1
	v_writelane_b32 v254, s79, 40
	s_branch .LBB0_685

; __global__ void __launch_bounds__(NWAVES * 64, 2) hybrid_fwd(Args args) {
;     ...
;             if (tid == 0) qslot[0] = nxt_ < 3072u ? (unsigned)ATT_ORDER[nxt_] : 0xffffffffu;
.LBB0_784:
	v_mbcnt_lo_u32_b32 v0, -1, 0
	v_mbcnt_hi_u32_b32 v0, -1, v0
	s_nop 0
	v_sub_u32_e32 v0, 0, v0
	v_cmp_eq_u32_e32 vcc, s11, v0
	s_and_saveexec_b64 s[4:5], vcc
	s_cbranch_execz .LBB0_684
	s_movk_i32 s6, 0xc00
	v_cmp_gt_u32_e32 vcc, s6, v208
	v_mov_b32_e32 v0, -1
	s_and_saveexec_b64 s[6:7], vcc
	s_cbranch_execz .LBB0_683
	v_mov_b32_e32 v209, v2
	s_mov_b32 s16, 0x21400
	v_lshl_add_u32 v0, v208, 1, s16
	ds_read_u16 v0, v0
	s_waitcnt lgkmcnt(0)
	s_branch .LBB0_683
